# pool mixer: each thread owns two adjacent token rows; second window sum = first + newest row - oldest row; 1/cnt formed up front; v_cvt_pk_bf16_f32 packs
# speedup vs baseline: 1.0327x; 1.0067x over previous
; __device__ __forceinline__ void mix_phase(LAS unsigned char* lds, const Params& p, const int layer) {
;     ...
;             if (prt) {
;                 const int t0 = r0 & 2047;
; #pragma unroll
;                 for (int k = 0; k < 3; ++k) { const int i = i0 + 16 * k; const float f = ((i < 47) && (t0 - 15 + i >= 0)) ? 1.0f : 0.0f; BF8_TO_F32(vw[k], a0, a1);
;                     if (i < 47) { *(LAS f32x4*)(SL + i * 264 + q * 8) = a0 * f; *(LAS f32x4*)(SL + i * 264 + q * 8 + 4) = a1 * f; } }
;             } else {
;                 const float* spool = p.in[2] + (size_t)layer * 128 * 15 * PW; const int bs0 = (r0 - NP) >> 3;
; #pragma unroll 2
;                 for (int i = tid >> 5; i < 92; i += 16) { const int sq = i / 23, ii = i - sq * 23; f32x4 a0, a1;
;                     if (ii < 15) { const float* sp = spool + ((size_t)(bs0 + sq) * 15 + ii) * PW + col; a0 = *(const f32x4*)sp; a1 = *(const f32x4*)(sp + 4); }
;                     else { const v4u vv = *(const v4u*)(PROJ + (size_t)(NP + (bs0 + sq) * 8 + (ii - 15)) * NC + C_UA + col); BF8_TO_F32(vv, c0_, c1_); a0 = c0_; a1 = c1_; }
;                     *(LAS f32x4*)(SL + i * 264 + q * 8) = a0; *(LAS f32x4*)(SL + i * 264 + q * 8 + 4) = a1; }
;             }
;             __syncthreads();
;             v2u sgc[2][2];
; #pragma unroll
;             for (int m = 0; m < 2; ++m)
; #pragma unroll
;                 for (int n = 0; n < 2; ++n) sgc[m][n] = sgv[m][n];
;             if (ua + G < NUA) MIX_PREFETCH_A(ua + G);
; #pragma unroll
;             for (int i = 0; i < 2; ++i) {
;                 const int rl = (tid >> 5) + 16 * i, bi = prt ? rl + 15 : (rl >> 3) * 23 + 15 + (rl & 7), t = (r0 + rl) & 2047;
;                 const LAS float* sp = SL + bi * 264 + q * 8;
;                 const f32x4 u0 = *(const LAS f32x4*)sp, u1 = *(const LAS f32x4*)(sp + 4);
;                 f32x4 s0 = u0, s1 = u1;
; #pragma unroll 4
;                 for (int j = 1; j < w; ++j) { s0 += *(const LAS f32x4*)(sp - j * 264); s1 += *(const LAS f32x4*)(sp - j * 264 + 4); }
;                 const int cnt = (prt && t + 1 < w) ? t + 1 : w; const float inv = 1.0f / (float)cnt;
;                 const f32x4 d0 = s0 * inv - u0, d1 = s1 * inv - u1;
;                 v4u o; o.x = pk2(d0[0], d0[1]); o.y = pk2(d0[2], d0[3]); o.z = pk2(d1[0], d1[1]); o.w = pk2(d1[2], d1[3]);
;                 *(LAS v4u*)(At + rl * 264 + q * 8) = o;
.LBB0_550:
	s_lshl_b32 s0, s56, 10
	s_mul_i32 s2, s56, 0x1e0000
	v_readlane_b32 s56, v251, 37
	v_or_b32_e32 v16, s46, v135
	s_mov_b32 s1, s80
	v_readlane_b32 s57, v251, 38
	v_ashrrev_i32_e32 v17, 31, v16
	v_readlane_b32 s12, v248, 35
	s_lshl_b64 s[0:1], s[0:1], 2
	v_readlane_b32 s58, v251, 39
	v_readlane_b32 s59, v251, 40
	v_readlane_b32 s60, v251, 41
	v_readlane_b32 s61, v251, 42
	v_readlane_b32 s62, v251, 43
	v_readlane_b32 s63, v251, 44
	v_readlane_b32 s64, v251, 45
	v_readlane_b32 s65, v251, 46
	v_readlane_b32 s66, v251, 47
	v_readlane_b32 s67, v251, 48
	v_readlane_b32 s68, v251, 49
	v_readlane_b32 s69, v251, 50
	v_readlane_b32 s70, v251, 51
	v_readlane_b32 s71, v251, 52
	s_mov_b64 s[36:37], s[56:57]
	v_lshlrev_b64 v[16:17], 9, v[16:17]
	v_readlane_b32 s13, v248, 36
	s_mov_b32 s3, s80
	s_add_u32 s5, s36, s0
	v_readlane_b32 s56, v251, 21
	v_lshl_add_u64 v[16:17], s[12:13], 0, v[16:17]
	v_lshlrev_b32_e32 v0, 4, v137
	s_addc_u32 s6, s37, s1
	s_lshl_b64 s[0:1], s[2:3], 2
	v_readlane_b32 s60, v251, 25
	v_readlane_b32 s61, v251, 26
	v_readlane_b32 s62, v251, 27
	v_readlane_b32 s63, v251, 28
	v_readlane_b32 s64, v251, 29
	v_readlane_b32 s65, v251, 30
	v_readlane_b32 s66, v251, 31
	v_readlane_b32 s67, v251, 32
	v_readlane_b32 s68, v251, 33
	v_readlane_b32 s69, v251, 34
	v_readlane_b32 s70, v251, 35
	v_readlane_b32 s71, v251, 36
	v_lshl_add_u64 v[16:17], v[16:17], 0, v[0:1]
	s_mov_b64 s[2:3], 0x7800000
	v_readlane_b32 s57, v251, 22
	v_readlane_b32 s58, v251, 23
	v_readlane_b32 s59, v251, 24
	s_mov_b64 s[70:71], s[66:67]
	v_lshl_add_u64 v[110:111], v[16:17], 0, s[2:3]
	s_movk_i32 s2, 0x5c
	s_mov_b64 s[68:69], s[64:65]
	s_mov_b64 s[66:67], s[62:63]
	s_mov_b64 s[64:65], s[60:61]
	v_cmp_gt_i32_e64 s[38:39], s2, v121
	v_lshl_add_u64 v[112:113], v[14:15], 1, s[74:75]
	v_readlane_b32 s2, v248, 8
	v_bfe_u32 v14, v130, 5, 3
	s_add_u32 s0, s64, s0
	v_add_u32_e32 v14, 15, v14
	v_add_u32_e32 v16, s2, v0
	v_lshrrev_b32_e32 v0, 8, v130
	s_addc_u32 s1, s65, s1
	v_lshl_add_u32 v15, v133, 1, s2
	s_movk_i32 s2, 0x420
	v_mad_i32_i24 v139, v0, 23, v14
	v_ashrrev_i32_e32 v0, 3, v131
	s_add_u32 s86, s12, 0x15304000
	v_mul_lo_u32 v138, v121, s2
	v_mul_lo_u32 v17, v131, s2
	v_mul_lo_u32 v19, v132, s2
	v_mad_u64_u32 v[114:115], s[2:3], v0, 23, v[14:15]
	s_addc_u32 s87, s13, 0
	s_lshl_b64 s[2:3], s[46:47], 2
	v_lshlrev_b32_e32 v134, 2, v137
	s_add_u32 s2, s5, s2
	s_addc_u32 s3, s6, s3
	v_lshlrev_b32_e32 v0, 2, v134
	v_lshl_add_u64 v[116:117], s[2:3], 0, v[0:1]
	v_max_i32_e32 v0, 0x4c, v121
	v_sub_u32_e32 v0, v0, v121
	v_add_u32_e32 v0, 15, v0
	v_and_b32_e32 v22, 16, v0
	s_mov_b32 s2, 0xb21642c9
	v_or_b32_e32 v137, s46, v134
	v_cmp_eq_u32_e64 s[46:47], 0, v22
	v_mul_hi_i32 v22, v121, s2
	v_add_u32_e32 v22, v22, v121
	v_lshrrev_b32_e32 v23, 31, v22
	v_ashrrev_i32_e32 v22, 4, v22
	s_movk_i32 s7, 0x210
	v_add_u32_e32 v141, v22, v23
	s_movk_i32 s2, 0xffe9
	v_lshl_add_u32 v136, v133, 2, 0
	v_mul_lo_u32 v20, v121, s7
	v_mul_lo_u32 v14, v131, s7
	v_mul_u32_u24_e32 v21, 0x210, v135
	v_mad_i32_i24 v118, v141, s2, v121
	v_cmp_lt_u32_e64 s[50:51], 15, v0
	v_lshlrev_b32_e32 v0, 5, v18
	v_readlane_b32 s2, v248, 9
	v_readlane_b32 s72, v248, 24
	v_cmp_gt_i32_e64 s[40:41], 47, v121
	v_cmp_gt_i32_e64 s[42:43], 31, v121
	v_cmp_gt_i32_e64 s[44:45], 15, v121
	s_movk_i32 s19, 0x420
	v_add_u32_e32 v140, 15, v121
	v_add_u32_e32 v115, 31, v121
	v_cmp_lt_i32_e64 s[30:31], 14, v118
	v_add_u32_e32 v142, 0x1ff1, v118
	v_ashrrev_i32_e32 v119, 31, v118
	v_add_u32_e32 v120, 0, v0
	v_add_u32_e32 v143, s2, v0
	s_mov_b32 s5, -1
	v_add_u32_e32 v144, v136, v17
	v_add_u32_e32 v145, v136, v19
	v_add_u32_e32 v146, v15, v20
	v_add_u32_e32 v147, v15, v14
	v_add_u32_e32 v146, v146, v20
	v_add_u32_e32 v147, 0x210, v146
	v_add_u32_e32 v140, v140, v121
	v_add_u32_e32 v115, 1, v140
	v_lshrrev_b32_e32 v149, 2, v121
	v_and_b32_e32 v150, 3, v121
	v_lshlrev_b32_e32 v150, 1, v150
	v_mad_u32_u24 v139, v149, 23, v150
	v_add_u32_e32 v139, 15, v139
	v_add_u32_e32 v114, 1, v139
	v_add_u32_e32 v148, v16, v21
	v_readlane_b32 s2, v249, 36
	v_readlane_b32 s3, v251, 0
	v_readlane_b32 s73, v248, 25
	s_mov_b64 s[62:63], s[58:59]
	s_mov_b64 s[60:61], s[56:57]

; #define LAS __attribute__((address_space(3)))
; __device__ __forceinline__ void mix_phase(LAS unsigned char* lds, const Params& p, const int layer) {
;     ...
;             for (int i = 0; i < 2; ++i) {
;                 const int rl = (tid >> 5) + 16 * i, bi = prt ? rl + 15 : (rl >> 3) * 23 + 15 + (rl & 7), t = (r0 + rl) & 2047;
;                 const LAS float* sp = SL + bi * 264 + q * 8;
;                 const f32x4 u0 = *(const LAS f32x4*)sp, u1 = *(const LAS f32x4*)(sp + 4);
;                 f32x4 s0 = u0, s1 = u1;
; #pragma unroll 4
;                 for (int j = 1; j < w; ++j) { s0 += *(const LAS f32x4*)(sp - j * 264); s1 += *(const LAS f32x4*)(sp - j * 264 + 4); }
;                 const int cnt = (prt && t + 1 < w) ? t + 1 : w; const float inv = 1.0f / (float)cnt;
.LBB0_585:
	s_lshl_b32 s13, 2, s12
	s_add_i32 s14, s13, -1
	v_lshl_add_u32 v0, v121, 1, s7
	v_and_b32_e32 v0, 0x7ff, v0
	v_add_u32_e32 v0, 1, v0
	v_min_u32_e32 v0, s13, v0
	v_mov_b32_e32 v149, s13
	v_cndmask_b32_e64 v0, v149, v0, s[52:53]
	v_cvt_f32_ubyte0_e32 v0, v0
	v_div_scale_f32 v149, s[16:17], v0, v0, 1.0
	v_rcp_f32_e32 v150, v149
	s_nop 0
	v_fma_f32 v151, -v149, v150, 1.0
	v_fmac_f32_e32 v150, v151, v150
	v_div_scale_f32 v151, vcc, 1.0, v0, 1.0
	v_mul_f32_e32 v152, v151, v150
	v_fma_f32 v153, -v149, v152, v151
	v_fmac_f32_e32 v152, v153, v150
	v_fma_f32 v149, -v149, v152, v151
	v_div_fmas_f32 v149, v149, v150, v152
	v_div_fixup_f32 v142, v149, v0, 1.0
	v_lshl_add_u32 v0, v121, 1, s7
	v_add_u32_e32 v0, 1, v0
	v_and_b32_e32 v0, 0x7ff, v0
	v_add_u32_e32 v0, 1, v0
	v_min_u32_e32 v0, s13, v0
	v_mov_b32_e32 v149, s13
	v_cndmask_b32_e64 v0, v149, v0, s[52:53]
	v_cvt_f32_ubyte0_e32 v0, v0
	v_div_scale_f32 v149, s[16:17], v0, v0, 1.0
	v_rcp_f32_e32 v150, v149
	s_nop 0
	v_fma_f32 v151, -v149, v150, 1.0
	v_fmac_f32_e32 v150, v151, v150
	v_div_scale_f32 v151, vcc, 1.0, v0, 1.0
	v_mul_f32_e32 v152, v151, v150
	v_fma_f32 v153, -v149, v152, v151
	v_fmac_f32_e32 v152, v153, v150
	v_fma_f32 v149, -v149, v152, v151
	v_div_fmas_f32 v149, v149, v150, v152
	v_div_fixup_f32 v143, v149, v0, 1.0
	v_cndmask_b32_e64 v0, v139, v140, s[52:53]
	v_mul_lo_u32 v0, v0, s19
	v_add_u32_e32 v86, v136, v0
	ds_read_b128 v[90:93], v86
	ds_read_b128 v[86:89], v86 offset:16
	v_add_u32_e32 v149, v120, v0
	v_add_u32_e32 v141, 0x420, v149
	v_add_u32_e32 v149, 0xfffff7c0, v149
	s_lshr_b32 s15, s14, 1
	s_waitcnt lgkmcnt(0)
	v_mov_b64_e32 v[100:101], v[92:93]
	v_mov_b64_e32 v[98:99], v[90:91]
	v_mov_b64_e32 v[96:97], v[88:89]
	v_mov_b64_e32 v[94:95], v[86:87]
	s_cmp_eq_u32 s15, 0
	s_cbranch_scc1 .Lpw_tail_a

; #define LAS __attribute__((address_space(3)))
; __device__ __forceinline__ unsigned pk2(float lo, float hi) { return f2bf(lo) | (f2bf(hi) << 16); }
; __device__ __forceinline__ void mix_phase(LAS unsigned char* lds, const Params& p, const int layer) {
;     ...
;                 const int rl = (tid >> 5) + 16 * i, bi = prt ? rl + 15 : (rl >> 3) * 23 + 15 + (rl & 7), t = (r0 + rl) & 2047;
;                 const LAS float* sp = SL + bi * 264 + q * 8;
;                 const f32x4 u0 = *(const LAS f32x4*)sp, u1 = *(const LAS f32x4*)(sp + 4);
;                 f32x4 s0 = u0, s1 = u1;
; #pragma unroll 4
;                 for (int j = 1; j < w; ++j) { s0 += *(const LAS f32x4*)(sp - j * 264); s1 += *(const LAS f32x4*)(sp - j * 264 + 4); }
;                 const int cnt = (prt && t + 1 < w) ? t + 1 : w; const float inv = 1.0f / (float)cnt;
;                 const f32x4 d0 = s0 * inv - u0, d1 = s1 * inv - u1;
;                 v4u o; o.x = pk2(d0[0], d0[1]); o.y = pk2(d0[2], d0[3]); o.z = pk2(d1[0], d1[1]); o.w = pk2(d1[2], d1[3]);
;                 *(LAS v4u*)(At + rl * 264 + q * 8) = o;
.Lpw_tail_a:
	ds_read_b128 v[150:153], v149 offset:1056
	ds_read_b128 v[154:157], v149 offset:1072
	ds_read_b128 v[158:161], v141
	ds_read_b128 v[252:255], v141 offset:16
	s_waitcnt lgkmcnt(2)
	v_pk_add_f32 v[100:101], v[100:101], v[152:153]
	v_pk_add_f32 v[98:99], v[98:99], v[150:151]
	v_pk_add_f32 v[96:97], v[96:97], v[156:157]
	v_pk_add_f32 v[94:95], v[94:95], v[154:155]
	v_mov_b32_e32 v0, v142
	v_pk_fma_f32 v[90:91], v[0:1], v[98:99], v[90:91] op_sel_hi:[0,1,1] neg_lo:[0,0,1] neg_hi:[0,0,1]
	v_pk_fma_f32 v[92:93], v[0:1], v[100:101], v[92:93] op_sel_hi:[0,1,1] neg_lo:[0,0,1] neg_hi:[0,0,1]
	v_pk_fma_f32 v[86:87], v[0:1], v[94:95], v[86:87] op_sel_hi:[0,1,1] neg_lo:[0,0,1] neg_hi:[0,0,1]
	v_pk_fma_f32 v[88:89], v[0:1], v[96:97], v[88:89] op_sel_hi:[0,1,1] neg_lo:[0,0,1] neg_hi:[0,0,1]
	v_cvt_pk_bf16_f32 v90, v90, v91
	v_cvt_pk_bf16_f32 v91, v92, v93
	v_cvt_pk_bf16_f32 v92, v86, v87
	v_cvt_pk_bf16_f32 v93, v88, v89
	ds_write_b128 v146, v[90:93]
	s_waitcnt lgkmcnt(1)
	v_pk_add_f32 v[98:99], v[98:99], v[158:159]
	v_pk_add_f32 v[100:101], v[100:101], v[160:161]
	v_pk_add_f32 v[94:95], v[94:95], v[252:253]
	v_pk_add_f32 v[96:97], v[96:97], v[254:255]
	v_pk_add_f32 v[98:99], v[98:99], v[150:151] neg_lo:[0,1] neg_hi:[0,1]
	v_pk_add_f32 v[100:101], v[100:101], v[152:153] neg_lo:[0,1] neg_hi:[0,1]
	v_pk_add_f32 v[94:95], v[94:95], v[154:155] neg_lo:[0,1] neg_hi:[0,1]
	v_pk_add_f32 v[96:97], v[96:97], v[156:157] neg_lo:[0,1] neg_hi:[0,1]
	v_mov_b32_e32 v0, v143
	v_pk_fma_f32 v[158:159], v[0:1], v[98:99], v[158:159] op_sel_hi:[0,1,1] neg_lo:[0,0,1] neg_hi:[0,0,1]
	v_pk_fma_f32 v[160:161], v[0:1], v[100:101], v[160:161] op_sel_hi:[0,1,1] neg_lo:[0,0,1] neg_hi:[0,0,1]
	v_pk_fma_f32 v[252:253], v[0:1], v[94:95], v[252:253] op_sel_hi:[0,1,1] neg_lo:[0,0,1] neg_hi:[0,0,1]
	v_pk_fma_f32 v[254:255], v[0:1], v[96:97], v[254:255] op_sel_hi:[0,1,1] neg_lo:[0,0,1] neg_hi:[0,0,1]
	v_cvt_pk_bf16_f32 v158, v158, v159
	v_cvt_pk_bf16_f32 v159, v160, v161
	v_cvt_pk_bf16_f32 v160, v252, v253
	v_cvt_pk_bf16_f32 v161, v254, v255
	ds_write_b128 v147, v[158:161]
	s_waitcnt lgkmcnt(0)
	s_barrier
; #define LAS __attribute__((address_space(3)))
; __device__ __forceinline__ unsigned pk2(float lo, float hi) { return f2bf(lo) | (f2bf(hi) << 16); }
; __device__ __forceinline__ float bflo(unsigned w) { return __uint_as_float(w << 16); }
; __device__ __forceinline__ float bfhi(unsigned w) { return __uint_as_float(w & 0xffff0000u); }
; __device__ __forceinline__ void mix_phase(LAS unsigned char* lds, const Params& p, const int layer) {
;     ...
;             __syncthreads();
;             f32x4 acc[2][2];
; #pragma unroll
;             for (int m = 0; m < 2; ++m)
; #pragma unroll
;                 for (int n = 0; n < 2; ++n) acc[m][n] = (f32x4){0.f, 0.f, 0.f, 0.f};
; #pragma unroll
;             for (int ks = 0; ks < 8; ++ks) {
;                 bf16x8 a[2];
; #pragma unroll
;                 for (int m = 0; m < 2; ++m) a[m] = *(const LAS bf16x8*)(At + (m * 16 + fr) * 264 + ks * 32 + fq * 8);
; #pragma unroll
;                 for (int m = 0; m < 2; ++m)
; #pragma unroll
;                     for (int n = 0; n < 2; ++n) acc[m][n] = __builtin_amdgcn_mfma_f32_16x16x32_bf16(b[n][ks], a[m], acc[m][n], 0, 0, 0);
;             }
;             bf16* YA = (bf16*)(ws + WS_YA);
; #pragma unroll
;             for (int m = 0; m < 2; ++m)
; #pragma unroll
;                 for (int n = 0; n < 2; ++n) { const int r = r0 + m * 16 + fr, ch = g * 256 + wid * 32 + n * 16 + fq * 4; const v2u sg = sgc[m][n];
;                     const f32x4 y = acc[m][n] * ps[n] * (f32x4){bflo(sg.x), bfhi(sg.x), bflo(sg.y), bfhi(sg.y)};
;                     v2u o; o.x = pk2(y[0], y[1]); o.y = pk2(y[2], y[3]); *(v2u*)(YA + (size_t)r * KCAT + ch) = o; }
	ds_read_b128 v[86:89], v148
	ds_read_b128 v[90:93], v148 offset:8448
	ds_read_b128 v[150:153], v148 offset:64
	ds_read_b128 v[154:157], v148 offset:8512
	s_waitcnt lgkmcnt(0)
	s_waitcnt vmcnt(15)
	v_mfma_f32_16x16x32_bf16 v[94:97], v[42:45], v[86:89], 0
	v_or_b32_e32 v0, s7, v135
	s_movk_i32 s12, 0x1800
	s_and_b64 vcc, exec, s[90:91]
	v_mfma_f32_16x16x32_bf16 v[86:89], v[74:77], v[86:89], 0
	v_mfma_f32_16x16x32_bf16 v[98:101], v[42:45], v[90:93], 0
	v_mfma_f32_16x16x32_bf16 v[90:93], v[74:77], v[90:93], 0
	v_mfma_f32_16x16x32_bf16 v[94:97], v[38:41], v[150:153], v[94:97]
	v_mfma_f32_16x16x32_bf16 v[86:89], v[70:73], v[150:153], v[86:89]
	v_mfma_f32_16x16x32_bf16 v[98:101], v[38:41], v[154:157], v[98:101]
	v_mfma_f32_16x16x32_bf16 v[90:93], v[70:73], v[154:157], v[90:93]
	ds_read_b128 v[150:153], v148 offset:128
	ds_read_b128 v[154:157], v148 offset:8576
	s_waitcnt lgkmcnt(1)
	v_mfma_f32_16x16x32_bf16 v[94:97], v[34:37], v[150:153], v[94:97]
	v_mfma_f32_16x16x32_bf16 v[86:89], v[66:69], v[150:153], v[86:89]
	s_waitcnt lgkmcnt(0)
	v_mfma_f32_16x16x32_bf16 v[98:101], v[34:37], v[154:157], v[98:101]
	v_mfma_f32_16x16x32_bf16 v[90:93], v[66:69], v[154:157], v[90:93]
	ds_read_b128 v[150:153], v148 offset:192
	ds_read_b128 v[154:157], v148 offset:8640
	s_waitcnt lgkmcnt(1)
	v_mfma_f32_16x16x32_bf16 v[94:97], v[30:33], v[150:153], v[94:97]
	s_waitcnt vmcnt(10)
	v_mfma_f32_16x16x32_bf16 v[86:89], v[62:65], v[150:153], v[86:89]
	s_waitcnt lgkmcnt(0)
	v_mfma_f32_16x16x32_bf16 v[98:101], v[30:33], v[154:157], v[98:101]
	v_mfma_f32_16x16x32_bf16 v[90:93], v[62:65], v[154:157], v[90:93]
	ds_read_b128 v[150:153], v148 offset:256
	ds_read_b128 v[154:157], v148 offset:8704
	s_waitcnt lgkmcnt(1)
	v_mfma_f32_16x16x32_bf16 v[94:97], v[26:29], v[150:153], v[94:97]
	v_mfma_f32_16x16x32_bf16 v[86:89], v[58:61], v[150:153], v[86:89]
	s_waitcnt lgkmcnt(0)
	v_mfma_f32_16x16x32_bf16 v[98:101], v[26:29], v[154:157], v[98:101]
	v_mfma_f32_16x16x32_bf16 v[90:93], v[58:61], v[154:157], v[90:93]
	ds_read_b128 v[150:153], v148 offset:320
	ds_read_b128 v[154:157], v148 offset:8768
	s_waitcnt lgkmcnt(1)
	v_mfma_f32_16x16x32_bf16 v[94:97], v[22:25], v[150:153], v[94:97]
	v_mfma_f32_16x16x32_bf16 v[86:89], v[54:57], v[150:153], v[86:89]
	s_waitcnt lgkmcnt(0)
	v_mfma_f32_16x16x32_bf16 v[98:101], v[22:25], v[154:157], v[98:101]
	v_mfma_f32_16x16x32_bf16 v[90:93], v[54:57], v[154:157], v[90:93]
	ds_read_b128 v[150:153], v148 offset:384
	ds_read_b128 v[154:157], v148 offset:8832
	s_waitcnt lgkmcnt(1)
	v_mfma_f32_16x16x32_bf16 v[94:97], v[18:21], v[150:153], v[94:97]
	v_mfma_f32_16x16x32_bf16 v[86:89], v[50:53], v[150:153], v[86:89]
	s_waitcnt lgkmcnt(0)
	v_mfma_f32_16x16x32_bf16 v[98:101], v[18:21], v[154:157], v[98:101]
	v_mfma_f32_16x16x32_bf16 v[90:93], v[50:53], v[154:157], v[90:93]
	ds_read_b128 v[150:153], v148 offset:448
	ds_read_b128 v[154:157], v148 offset:8896
	s_waitcnt lgkmcnt(1)
	v_mfma_f32_16x16x32_bf16 v[94:97], v[14:17], v[150:153], v[94:97]
	s_waitcnt lgkmcnt(0)
	v_mfma_f32_16x16x32_bf16 v[98:101], v[14:17], v[154:157], v[98:101]
	s_nop 5
	v_mul_f32_e64 v94, v82, v94
	v_mul_f32_e64 v95, v83, v95
	v_pk_mul_f32 v[96:97], v[84:85], v[96:97]
	v_mfma_f32_16x16x32_bf16 v[90:93], v[46:49], v[154:157], v[90:93]
	s_waitcnt vmcnt(7)
	v_lshlrev_b32_e32 v156, 16, v108
	v_and_b32_e32 v157, 0xffff0000, v108
	v_lshlrev_b32_e32 v108, 16, v109
	v_and_b32_e32 v109, 0xffff0000, v109
	v_pk_mul_f32 v[94:95], v[94:95], v[156:157]
	v_pk_mul_f32 v[96:97], v[96:97], v[108:109]
	v_bfe_u32 v108, v94, 16, 1
	v_add3_u32 v94, v94, v108, s26
	v_bfe_u32 v108, v95, 16, 1
	v_lshrrev_b32_e32 v94, 16, v94
	v_add3_u32 v95, v95, v108, s26
	v_and_or_b32 v94, v95, s24, v94
	v_bfe_u32 v95, v96, 16, 1
	v_mfma_f32_16x16x32_bf16 v[86:89], v[46:49], v[150:153], v[86:89]
	v_add_u32_e32 v150, s6, v137
	v_add3_u32 v95, v96, v95, s26
	v_bfe_u32 v96, v97, 16, 1
	v_mov_b64_e32 v[152:153], s[86:87]
	v_lshrrev_b32_e32 v95, 16, v95
	v_add3_u32 v96, v97, v96, s26
	v_ashrrev_i32_e32 v151, 31, v150
	v_mad_i64_i32 v[154:155], s[6:7], v0, s12, v[152:153]
	v_and_or_b32 v95, v96, s24, v95
	v_lshlrev_b64 v[96:97], 1, v[150:151]
	v_lshl_add_u64 v[108:109], v[154:155], 0, v[96:97]
	global_store_dwordx2 v[108:109], v[94:95], off
	v_pk_mul_f32 v[86:87], v[78:79], v[86:87]
	s_waitcnt vmcnt(5)
	v_lshlrev_b32_e32 v94, 16, v106
	v_and_b32_e32 v95, 0xffff0000, v106
	v_pk_mul_f32 v[86:87], v[86:87], v[94:95]
	v_pk_mul_f32 v[88:89], v[80:81], v[88:89]
	v_bfe_u32 v94, v86, 16, 1
	v_lshlrev_b32_e32 v106, 16, v107
	v_and_b32_e32 v107, 0xffff0000, v107
	v_add3_u32 v86, v86, v94, s26
	v_bfe_u32 v94, v87, 16, 1
	v_pk_mul_f32 v[88:89], v[88:89], v[106:107]
	v_lshrrev_b32_e32 v86, 16, v86
	v_add3_u32 v87, v87, v94, s26
	v_and_or_b32 v86, v87, s24, v86
	v_bfe_u32 v87, v88, 16, 1
	v_add3_u32 v87, v88, v87, s26
	v_bfe_u32 v88, v89, 16, 1
	v_lshrrev_b32_e32 v87, 16, v87
	v_add3_u32 v88, v89, v88, s26
	v_pk_mul_f32 v[94:95], v[82:83], v[98:99]
	v_lshlrev_b32_e32 v98, 16, v104
	v_and_b32_e32 v99, 0xffff0000, v104
	v_and_or_b32 v87, v88, s24, v87
	v_or_b32_e32 v0, 16, v0
	v_pk_mul_f32 v[94:95], v[94:95], v[98:99]
	global_store_dwordx2 v[108:109], v[86:87], off offset:32
	v_mad_i64_i32 v[86:87], s[6:7], v0, s12, v[152:153]
	v_bfe_u32 v0, v94, 16, 1
	v_pk_mul_f32 v[88:89], v[84:85], v[100:101]
	v_lshlrev_b32_e32 v100, 16, v105
	v_and_b32_e32 v101, 0xffff0000, v105
	v_add3_u32 v0, v94, v0, s26
	v_bfe_u32 v94, v95, 16, 1
	v_pk_mul_f32 v[88:89], v[88:89], v[100:101]
	v_lshrrev_b32_e32 v0, 16, v0
	v_add3_u32 v94, v95, v94, s26
	v_and_or_b32 v94, v94, s24, v0
	v_bfe_u32 v0, v88, 16, 1
	v_add3_u32 v0, v88, v0, s26
	v_bfe_u32 v88, v89, 16, 1
	v_lshrrev_b32_e32 v0, 16, v0
	v_add3_u32 v88, v89, v88, s26
	v_and_or_b32 v95, v88, s24, v0
	v_pk_mul_f32 v[88:89], v[80:81], v[92:93]
	v_pk_mul_f32 v[90:91], v[78:79], v[90:91]
	v_lshlrev_b32_e32 v92, 16, v102
	v_and_b32_e32 v93, 0xffff0000, v102
	v_pk_mul_f32 v[90:91], v[90:91], v[92:93]
	v_lshl_add_u64 v[86:87], v[86:87], 0, v[96:97]
	v_bfe_u32 v0, v90, 16, 1
	global_store_dwordx2 v[86:87], v[94:95], off
	v_lshlrev_b32_e32 v94, 16, v103
	v_and_b32_e32 v95, 0xffff0000, v103
	v_add3_u32 v0, v90, v0, s26
	v_bfe_u32 v90, v91, 16, 1
	v_pk_mul_f32 v[88:89], v[88:89], v[94:95]
	v_lshrrev_b32_e32 v0, 16, v0
	v_add3_u32 v90, v91, v90, s26
	v_and_or_b32 v90, v90, s24, v0
	v_bfe_u32 v0, v88, 16, 1
	v_add3_u32 v0, v88, v0, s26
	v_bfe_u32 v88, v89, 16, 1
	v_lshrrev_b32_e32 v0, 16, v0
	v_add3_u32 v88, v89, v88, s26
	v_readlane_b32 s6, v249, 62
	v_and_or_b32 v91, v88, s24, v0
	s_add_i32 s2, s2, s6
	s_waitcnt vmcnt(4)
	v_mov_b64_e32 v[102:103], v[126:127]
	v_mov_b64_e32 v[104:105], v[124:125]
	s_waitcnt vmcnt(3)
	v_mov_b64_e32 v[106:107], v[128:129]
	v_mov_b64_e32 v[108:109], v[122:123]
	global_store_dwordx2 v[86:87], v[90:91], off offset:32
	s_cbranch_vccz .LBB0_551
